# attention D loop: softmax row-sum via packed tree adds (14 fewer VALU per half tile)
# speedup vs baseline: 1.0029x; 1.0029x over previous
; DI void attn_item(const Params& P, unsigned char* smem, bool samp, int b, int c) {
;     ...
;       const float mcur = mrun[qh];
;       float ps = 0.f;
;       for (int r = 0; r < 16; ++r) {
;         const float p = __builtin_amdgcn_exp2f(sacc[qh][r] - mcur);
;         sacc[qh][r] = p;
;         ps += p;
;       }
;       lrun[qh] += ps;
.LBB0_709:
	v_pk_add_f32 v[92:93], v[92:93], v[94:95]
	v_pk_add_f32 v[6:7], v[6:7], v[8:9]
	v_pk_add_f32 v[96:97], v[96:97], v[98:99]
	v_pk_add_f32 v[10:11], v[10:11], v[12:13]
	v_pk_add_f32 v[84:85], v[84:85], v[86:87]
	v_pk_add_f32 v[14:15], v[14:15], v[16:17]
	v_add_f32_e32 v100, v100, v91
	v_add_f32_e32 v5, v5, v90
	v_pk_add_f32 v[92:93], v[92:93], v[96:97]
	v_pk_add_f32 v[6:7], v[6:7], v[10:11]
	v_pk_add_f32 v[82:83], v[82:83], v[84:85]
	v_pk_add_f32 v[14:15], v[14:15], v[88:89]
	v_pk_add_f32 v[92:93], v[92:93], v[82:83]
	v_pk_add_f32 v[6:7], v[6:7], v[14:15]
	s_add_i32 s8, s8, 32
	v_add_f32_e32 v92, v92, v93
	v_add_f32_e32 v6, v6, v7
	v_add_f32_e32 v92, v92, v100
	v_add_f32_e32 v5, v5, v6
	v_add_f32_e32 v197, v197, v92
	v_add_f32_e32 v4, v4, v5
	v_lshl_add_u64 v[178:179], v[178:179], 0, s[82:83]
	v_lshl_add_u64 v[180:181], v[180:181], 0, s[82:83]
	v_add_u32_e32 v199, 0x80, v199
	s_cmp_eq_u32 s9, s11
	v_add_u32_e32 v200, 0x100, v200
	s_cbranch_scc1 .LBB0_711
	s_mov_b32 s2, s11
	s_branch .LBB0_697
